# PRO weight-transpose loop: gain multiply deferred to next iteration top so tile loads stay in flight (no vmcnt(0) after loads)
# speedup vs baseline: 1.0097x; 1.0097x over previous
.LBB0_623:
	v_lshlrev_b32_e32 v14, 4, v208
	v_and_b32_e32 v14, 0xf0, v14
	v_lshlrev_b32_e32 v15, 3, v208
	s_movk_i32 s18, 0x104
	v_add_u32_e32 v17, 0, v14
	v_ashrrev_i32_e32 v14, 3, v208
	v_and_b32_e32 v16, 56, v15
	v_mul_lo_u32 v21, v10, s18
	s_add_u32 s18, s24, 0x14280000
	v_lshl_add_u32 v18, v14, 2, 0
	v_mul_u32_u24_e32 v19, 0x104, v16
	s_addc_u32 s19, s25, 0
	s_add_i32 s20, s28, s12
	v_ashrrev_i32_e32 v15, 31, v14
	s_lshl_b32 s21, s20, 6
	s_lshl_b32 s22, s12, 6
	s_lshl_b32 s23, s20, 2
	s_lshl_b32 s29, s12, 2
	v_add_u32_e32 v21, v17, v21
	v_add_u32_e32 v22, v18, v19
	v_lshlrev_b32_e32 v16, 1, v16
	s_mov_b32 s44, s28
	s_mov_b64 s[30:31], s[26:27]
	s_mov_b32 s45, s17
	s_mov_b64 s[50:51], 0
	s_waitcnt vmcnt(0)
	s_branch .LBB0_625

.LBB0_625:
	v_add_u32_e32 v17, 0x2080, v21
	s_waitcnt vmcnt(1)
	s_and_b64 vcc, exec, s[50:51]
	s_cbranch_vccz .Lpro_nogain
	v_pk_mul_f32 v[4:5], v[4:5], v[32:33] op_sel_hi:[1,0]
	v_pk_mul_f32 v[2:3], v[2:3], v[32:33] op_sel_hi:[1,0]
	v_pk_mul_f32 v[8:9], v[8:9], v[36:37] op_sel_hi:[1,0]
	v_pk_mul_f32 v[6:7], v[6:7], v[36:37] op_sel_hi:[1,0]
.Lpro_nogain:
	ds_write2_b32 v21, v2, v3 offset1:1
	ds_write2_b32 v21, v4, v5 offset0:2 offset1:3
	ds_write2_b32 v17, v6, v7 offset1:1
	v_add_u32_e32 v17, 0x2088, v21
	ds_write2_b32 v17, v8, v9 offset1:1
	s_waitcnt lgkmcnt(0)
	s_barrier
	s_cmpk_gt_i32 s20, 0x28ff
	s_cbranch_scc1 .LBB0_624
	s_cmpk_gt_i32 s20, 0x15ff
	s_mov_b64 s[42:43], -1
	s_cbranch_scc0 .LBB0_639
	s_cmpk_gt_u32 s20, 0x20ff
	s_cbranch_scc0 .LBB0_636
	s_cmpk_gt_u32 s20, 0x26ff
	s_mov_b64 s[38:39], -1
	s_cbranch_scc0 .LBB0_630
	s_add_i32 s30, s20, 0xffffd900
	s_lshr_b32 s30, s30, 8
	s_mov_b32 s31, s80
	s_lshl_b64 s[36:37], s[30:31], 22
	s_add_u32 s36, s64, s36
	s_addc_u32 s37, s65, s37
	s_and_b32 s38, s21, 0x3c0
	s_lshl_b32 s39, s38, 12
	s_add_u32 s36, s36, s39
	s_addc_u32 s37, s37, 0
	s_and_b32 s39, s23, 0x3c0
	s_lshl_b32 s40, s39, 2
	s_add_u32 s36, s36, s40
	s_addc_u32 s37, s37, 0
	s_lshl_b64 s[30:31], s[30:31], 21
	s_add_u32 s30, s15, s30
	s_addc_u32 s31, s16, s31
	s_lshl_b32 s39, s39, 11
	s_add_u32 s30, s30, s39
	s_addc_u32 s31, s31, 0
	s_lshl_b32 s38, s38, 1
	s_add_u32 s30, s30, s38
	s_addc_u32 s31, s31, 0
	s_mov_b64 s[38:39], 0

.LBB0_641:
	v_lshl_add_u64 v[6:7], s[36:37], 0, v[0:1]
	v_mul_lo_u32 v4, s41, v10
	v_mul_lo_u32 v5, s40, v11
	v_mad_u64_u32 v[2:3], s[36:37], s40, v10, 0
	v_add3_u32 v3, v3, v5, v4
	v_lshl_add_u64 v[2:3], v[2:3], 2, v[6:7]
	global_load_dwordx4 v[2:5], v[2:3], off
	s_cmp_lg_u64 s[38:39], 0
	s_cselect_b64 s[36:37], -1, 0
	s_mov_b64 s[50:51], s[36:37]
	s_cmp_eq_u64 s[38:39], 0
	v_lshl_add_u64 v[18:19], v[10:11], 2, s[38:39]
	s_cbranch_scc1 .LBB0_643
	global_load_dword v32, v[18:19], off
.LBB0_643:
	v_mul_lo_u32 v17, s41, v12
	v_mul_lo_u32 v23, s40, v13
	v_mad_u64_u32 v[8:9], s[38:39], s40, v12, 0
	v_add3_u32 v9, v9, v23, v17
	v_lshl_add_u64 v[6:7], v[8:9], 2, v[6:7]
	global_load_dwordx4 v[6:9], v[6:7], off
	s_andn2_b64 vcc, exec, s[36:37]
	s_cbranch_vccnz .LBB0_624
	global_load_dword v36, v[18:19], off offset:128
	s_branch .LBB0_624
